# MLA: XOR-swizzled conflict-free LDS tiles, fewer waits/nops, cheaper cross-lane max
# baseline (speedup 1.0000x reference)
; #define LAS __attribute__((address_space(3)))
; __device__ __forceinline__ void mla_unit(const Ctx& C, const Params& p, int unit) {
;     ...
;     for (int g = 0; g < 2; ++g) {
;         const size_t qrow = tok0 + q0w + 16 * g + fr;
;         const bf16* qp = QM + qrow * 768 + h * 96 + fq * 8;
;         qf[g][0] = *(const bf16x8*)qp; qf[g][1] = *(const bf16x8*)(qp + 32);
;         const v4u raw = *(const v4u*)(qp + 64);
;         const f32x2* cs = (const f32x2*)(p.ws + WS_ROPE) + qrow * 16 + (fq & 1) * 8;
;         const float own[8] = {bflo(raw.x), bfhi(raw.x), bflo(raw.y), bfhi(raw.y), bflo(raw.z), bfhi(raw.z), bflo(raw.w), bfhi(raw.w)};
;         float res[8];
; #pragma unroll
;     ...
;     const int nt = 4 * (qb + 1), my_last = (q0w + 31) >> 6;
;     const int kc0 = tid, kc1 = tid + 512;
;     const int key0 = kc0 / 12, part0 = kc0 % 12, key1 = kc1 / 12, part1 = kc1 % 12; const bool has1 = kc1 < 768;
;     const bf16* ksrc0 = (part0 < 8) ? (KM + (tok0 + key0) * 512 + h * 64 + part0 * 8) : (P + (tok0 + key0) * PN + C_KPE + (part0 - 8) * 8);
;     const bf16* ksrc1 = (part1 < 8) ? (KM + (tok0 + key1) * 512 + h * 64 + part1 * 8) : (P + (tok0 + key1) * PN + C_KPE + (part1 - 8) * 8);
;     const size_t kstep0 = (part0 < 8) ? (size_t)64 * 512 : (size_t)64 * PN, kstep1 = (part1 < 8) ? (size_t)64 * 512 : (size_t)64 * PN;
;     const int kdst0 = key0 * AK_ROW + part0 * 16, kdst1 = key1 * AK_ROW + part1 * 16;
;     const bf16* vsrc = VTM + (size_t)(h * 64 + (tid >> 3)) * T + tok0 + (tid & 7) * 8;
;     const int vdst = AK_BYTES + (tid >> 3) * AV_ROW + ((((tid & 7) >> 2) * 32 + (2 * (tid & 1)) * 8 + (((tid & 7) >> 1) & 1) * 4) * 2);
;     LAS unsigned char* lds = C.lds;
;     v4u r0[2], r1[2], r2[2];
; #pragma unroll
;     for (int sb = 0; sb < 2; ++sb) { r1[sb] = (v4u){0u, 0u, 0u, 0u}; r0[sb] = *(const v4u*)(ksrc0 + (size_t)sb * kstep0); if (has1) r1[sb] = *(const v4u*)(ksrc1 + (size_t)sb * kstep1); r2[sb] = *(const v4u*)(vsrc + (size_t)sb * 64); }
; #pragma unroll
;     for (int sb = 0; sb < 2; ++sb) { LAS unsigned char* nb = lds + sb * ABUF; *(LAS v4u*)(nb + kdst0) = r0[sb]; if (has1) *(LAS v4u*)(nb + kdst1) = r1[sb]; { const v4u vv_ = r2[sb]; *(LAS v2u*)(nb + vdst) = (v2u){vv_.x, vv_.y}; *(LAS v2u*)(nb + vdst + 16) = (v2u){vv_.z, vv_.w}; } }
;     __syncthreads();
.LBB0_499:
	s_or_b64 exec, exec, s[20:21]
	s_movk_i32 s10, 0xd0
	v_mul_lo_u32 v0, v40, s10
	v_mov_b32_e32 v248, v40
	v_mov_b32_e32 v249, v53
	s_movk_i32 s10, 0x90
	v_lshlrev_b32_e32 v40, 5, v50
	v_lshl_add_u32 v3, v53, 4, v0
	v_mul_lo_u32 v0, v41, s10
	v_and_b32_e32 v2, 64, v42
	v_and_b32_e32 v40, 32, v40
	v_and_b32_e32 v41, 8, v51
	v_or3_b32 v2, v41, v40, v2
	global_load_dwordx4 v[40:43], v[128:129], off offset:128
	v_add_u32_e32 v53, 0, v3
	v_add_u32_e32 v187, v0, v2
	v_lshrrev_b32_e32 v198, 2, v249
	v_lshrrev_b32_e32 v199, 4, v248
	v_lshl_add_u32 v198, v198, 2, v199
	v_and_b32_e32 v199, 15, v248
	v_and_b32_e32 v200, 3, v249
	v_lshlrev_b32_e32 v199, 6, v199
	v_lshl_or_b32 v199, v200, 4, v199
	v_bfe_u32 v200, v248, 3, 1
	v_lshlrev_b32_e32 v200, 5, v200
	v_xor_b32_e32 v199, v199, v200
	v_lshl_add_u32 v3, v198, 10, v199
	v_mov_b32_e32 v53, v3
	v_bfe_u32 v198, v185, 2, 1
	v_lshrrev_b32_e32 v199, 7, v185
	v_lshl_add_u32 v198, v198, 2, v199
	v_bfe_u32 v199, v185, 3, 4
	v_lshlrev_b32_e32 v199, 6, v199
	v_and_b32_e32 v200, 1, v185
	v_lshl_or_b32 v199, v200, 5, v199
	v_bfe_u32 v200, v185, 1, 1
	v_lshl_or_b32 v199, v200, 3, v199
	v_bfe_u32 v200, v185, 6, 1
	v_lshlrev_b32_e32 v200, 5, v200
	v_xor_b32_e32 v199, v199, v200
	v_lshl_add_u32 v187, v198, 10, v199
	s_waitcnt vmcnt(3)
	ds_write_b128 v53, v[20:23]
	s_and_saveexec_b64 s[10:11], s[0:1]
	s_xor_b64 s[0:1], exec, s[10:11]
	s_cbranch_execz .LBB0_501
	v_add_u32_e32 v0, 0, v187
	v_add_u32_e32 v0, 0x3000, v0
	s_waitcnt vmcnt(2)
	ds_write2_b64 v0, v[32:33], v[34:35] offset0:128 offset1:130
.LBB0_501:
	s_or_saveexec_b64 s[0:1], s[0:1]
	s_movk_i32 s10, 0xd0
	v_mul_lo_u32 v0, v48, s10
	s_waitcnt vmcnt(1)
	v_mov_b64_e32 v[50:51], v[38:39]
	v_lshl_add_u32 v189, v52, 4, v0
	v_lshrrev_b32_e32 v198, 2, v52
	v_lshrrev_b32_e32 v199, 4, v48
	v_lshl_add_u32 v198, v198, 2, v199
	v_and_b32_e32 v199, 15, v48
	v_and_b32_e32 v200, 3, v52
	v_lshlrev_b32_e32 v199, 6, v199
	v_lshl_or_b32 v199, v200, 4, v199
	v_bfe_u32 v200, v48, 3, 1
	v_lshlrev_b32_e32 v200, 5, v200
	v_xor_b32_e32 v199, v199, v200
	v_lshl_add_u32 v189, v198, 10, v199
	v_mov_b32_e32 v0, v3
	v_mov_b64_e32 v[48:49], v[36:37]
	s_xor_b64 exec, exec, s[0:1]
	s_cbranch_execz .LBB0_503
	v_add_u32_e32 v0, 0, v189
	ds_write_b128 v0, v[24:27]
	v_add_u32_e32 v0, 0, v187
	v_add_u32_e32 v0, 0x3000, v0
	v_mov_b64_e32 v[50:51], v[30:31]
	ds_write2_b64 v0, v[32:33], v[34:35] offset0:128 offset1:130
	ds_write_b128 v53, v[36:39] offset:22528
	v_mov_b32_e32 v0, v189
	v_mov_b64_e32 v[48:49], v[28:29]
.LBB0_503:
	s_or_b64 exec, exec, s[0:1]
	v_add_u32_e32 v0, 0, v0
	ds_write_b128 v0, v[48:51] offset:22528
	v_add_u32_e32 v0, 0, v187
	v_add_u32_e32 v0, 0x8800, v0
	s_mov_b64 s[0:1], -1
	s_cmp_lg_u32 s31, 16
	v_lshlrev_b32_e32 v188, 2, v193
	s_waitcnt vmcnt(0)
	ds_write2_b64 v0, v[40:41], v[42:43] offset0:128 offset1:130
	s_waitcnt lgkmcnt(0)
	s_barrier
	s_cbranch_scc0 .LBB0_533
	v_mov_b32_e32 v49, v106
	v_mov_b32_e32 v106, v105
	v_pk_mul_f32 v[50:51], v[106:107], v[172:173]
	v_cmp_gt_u32_e32 vcc, 2, v193
	v_mov_b32_e32 v48, v104
	s_lshl_b32 s0, s31, 2
	v_cndmask_b32_e64 v51, v51, -v51, vcc
	v_cndmask_b32_e64 v50, v50, -v50, vcc
	v_pk_fma_f32 v[48:49], v[48:49], v[170:171], v[50:51]
	v_mov_b32_e32 v51, v102
	v_mov_b32_e32 v102, v101
	v_pk_mul_f32 v[52:53], v[102:103], v[168:169]
	v_mov_b32_e32 v50, v100
	v_cndmask_b32_e64 v53, v53, -v53, vcc
	v_cndmask_b32_e64 v52, v52, -v52, vcc
	v_pk_fma_f32 v[50:51], v[50:51], v[166:167], v[52:53]
	v_mov_b32_e32 v53, v98
	v_mov_b32_e32 v98, v97
	v_pk_mul_f32 v[54:55], v[98:99], v[164:165]
	v_mov_b32_e32 v52, v96
	v_cndmask_b32_e64 v55, v55, -v55, vcc
	v_cndmask_b32_e64 v54, v54, -v54, vcc
	v_pk_fma_f32 v[52:53], v[52:53], v[162:163], v[54:55]
	v_mov_b32_e32 v55, v46
	v_mov_b32_e32 v46, v45
	v_mov_b32_e32 v54, v44
	v_pk_mul_f32 v[44:45], v[46:47], v[160:161]
	v_cvt_pk_bf16_f32 v46, v52, v53
	v_cndmask_b32_e64 v45, v45, -v45, vcc
	v_cndmask_b32_e64 v44, v44, -v44, vcc
	v_pk_fma_f32 v[54:55], v[54:55], v[158:159], v[44:45]
	v_cvt_pk_bf16_f32 v44, v48, v49
	v_mov_b32_e32 v49, v94
	v_mov_b32_e32 v94, v93
	v_cvt_pk_bf16_f32 v45, v50, v51
	v_pk_mul_f32 v[50:51], v[94:95], v[156:157]
	v_mov_b32_e32 v48, v92
	v_cndmask_b32_e64 v51, v51, -v51, vcc
	v_cndmask_b32_e64 v50, v50, -v50, vcc
	v_pk_fma_f32 v[48:49], v[48:49], v[154:155], v[50:51]
	v_mov_b32_e32 v51, v90
	v_mov_b32_e32 v90, v89
	v_pk_mul_f32 v[52:53], v[90:91], v[152:153]
	v_mov_b32_e32 v50, v88
	v_cndmask_b32_e64 v53, v53, -v53, vcc
	v_cndmask_b32_e64 v52, v52, -v52, vcc
	v_pk_fma_f32 v[50:51], v[50:51], v[150:151], v[52:53]
	v_mov_b32_e32 v53, v86
	v_mov_b32_e32 v86, v85
	v_cvt_pk_bf16_f32 v47, v54, v55
	v_pk_mul_f32 v[54:55], v[86:87], v[114:115]
	v_mov_b32_e32 v52, v84
	v_cndmask_b32_e64 v55, v55, -v55, vcc
	v_cndmask_b32_e64 v54, v54, -v54, vcc
	v_pk_fma_f32 v[52:53], v[52:53], v[112:113], v[54:55]
	v_mov_b32_e32 v55, v62
	v_mov_b32_e32 v62, v61
	s_sub_i32 s31, 64, s0
	s_and_b32 s0, s4, 0x3ffffffc
	v_pk_mul_f32 v[56:57], v[62:63], v[110:111]
	s_or_b32 s0, s35, s0
	v_mov_b32_e32 v54, v60
	v_cndmask_b32_e64 v57, v57, -v57, vcc
	v_cndmask_b32_e64 v56, v56, -v56, vcc
	s_lshl_b32 s0, s0, 2
	v_pk_fma_f32 v[54:55], v[54:55], v[108:109], v[56:57]
	s_sub_i32 s0, 64, s0
	v_mov_b32_e32 v76, v1
	v_mov_b32_e32 v77, v1
	v_mov_b32_e32 v78, v1
	v_mov_b32_e32 v79, v1
	v_cvt_pk_bf16_f32 v60, v48, v49
	v_cvt_pk_bf16_f32 v61, v50, v51
	v_cvt_pk_bf16_f32 v62, v52, v53
	v_cvt_pk_bf16_f32 v63, v54, v55
	s_addk_i32 s34, 0xf1f
	v_or_b32_e32 v151, s30, v192
	s_lshr_b32 s0, s0, 1
	v_mov_b64_e32 v[56:57], v[76:77]
	v_mov_b64_e32 v[48:49], v[76:77]
	v_mov_b64_e32 v[52:53], v[76:77]
	v_mov_b64_e32 v[82:83], v[78:79]
	v_mov_b64_e32 v[68:69], v[76:77]
	v_mov_b64_e32 v[64:65], v[76:77]
	v_mov_b64_e32 v[72:73], v[76:77]
	s_ashr_i32 s34, s34, 6
	v_lshlrev_b32_e32 v0, 2, v193
	s_max_u32 s35, s0, 1
	v_mul_u32_u24_e32 v153, 0xd0, v192
	v_or_b32_e32 v155, 16, v151
	v_add_u32_e32 v156, 14, v151
	v_add_u32_e32 v157, 13, v151
	v_mul_u32_u24_e32 v158, 0x90, v192
	v_lshl_add_u32 v159, v193, 4, 0
	v_lshlrev_b32_e32 v246, 6, v192
	v_lshl_or_b32 v246, v193, 4, v246
	v_bfe_u32 v247, v192, 3, 1
	v_lshlrev_b32_e32 v247, 5, v247
	v_xor_b32_e32 v246, v246, v247
	s_mov_b32 s90, 0
	v_mov_b32_e32 v152, 0xf149f2ca
	v_mov_b32_e32 v190, 0
	v_mov_b64_e32 v[58:59], v[78:79]
	v_mov_b64_e32 v[50:51], v[78:79]
	v_mov_b64_e32 v[54:55], v[78:79]
	v_mov_b64_e32 v[80:81], v[76:77]
	v_mov_b64_e32 v[70:71], v[78:79]
	v_mov_b64_e32 v[66:67], v[78:79]
	v_mov_b64_e32 v[74:75], v[78:79]
	v_mov_b32_e32 v191, 0
	v_mov_b32_e32 v154, 0xf149f2ca

; #define LAS __attribute__((address_space(3)))
; __device__ __forceinline__ void mla_unit(const Ctx& C, const Params& p, int unit) {
;     ...
;             const LAS unsigned char* Kb = lds + ((kp & 1) * 2 + sub) * ABUF; const LAS unsigned char* Vb = Kb + AK_BYTES;
;             const int k0 = kt * 64;
;             f32x4 s[2][4];
; #pragma unroll
;             for (int g = 0; g < 2; ++g)
; #pragma unroll
;                 for (int blk = 0; blk < 4; ++blk) s[g][blk] = (f32x4){0.f, 0.f, 0.f, 0.f};
; #pragma unroll
;             for (int kk = 0; kk < 3; ++kk)
; #pragma unroll
;                 for (int blk = 0; blk < 4; ++blk) {
;                     const bf16x8 kf = *(const LAS bf16x8*)(Kb + (blk * 16 + fr) * AK_ROW + (kk * 32 + fq * 8) * 2);
; #pragma unroll
;                     for (int g = 0; g < 2; ++g) s[g][blk] = __builtin_amdgcn_mfma_f32_16x16x32_bf16(kf, qf[g][kk], s[g][blk], 0, 0, 0);
;                 }
;             const bool need_mask = (k0 + 63 > q0w);
;             bf16x8 pf[2][2];
; #pragma unroll
;             for (int g = 0; g < 2; ++g) {
;                 const int qi = q0w + 16 * g + fr;
;                 if (need_mask) {
;                     asm volatile("" ::: "memory");
; #pragma unroll
;                     for (int blk = 0; blk < 4; ++blk)
; #pragma unroll
;                         for (int j = 0; j < 4; ++j) { const int key = k0 + blk * 16 + fq * 4 + j; if (key > qi) s[g][blk][j] = -1e30f; }
;                     asm volatile("" ::: "memory");
;                 }
.LBB0_514:
	s_or_b32 s1, s4, s88
	s_mulk_i32 s1, 0x5800
	v_add_u32_e32 v2, s1, v246
	ds_read_b128 v[198:201], v2
	ds_read_b128 v[210:213], v2 offset:1024
	ds_read_b128 v[222:225], v2 offset:2048
	ds_read_b128 v[234:237], v2 offset:3072
	ds_read_b128 v[202:205], v2 offset:4096
	ds_read_b128 v[214:217], v2 offset:5120
	ds_read_b128 v[226:229], v2 offset:6144
	ds_read_b128 v[238:241], v2 offset:7168
	ds_read_b128 v[206:209], v2 offset:8192
	ds_read_b128 v[218:221], v2 offset:9216
	ds_read_b128 v[230:233], v2 offset:10240
	ds_read_b128 v[242:245], v2 offset:11264
	s_lshl_b32 s0, s0, 6
	s_or_b32 s1, s0, 63
	s_waitcnt lgkmcnt(8)
	v_mfma_f32_16x16x32_bf16 v[84:87], v[198:201], v[12:15], 0
	v_mfma_f32_16x16x32_bf16 v[100:103], v[198:201], v[16:19], 0
	v_mfma_f32_16x16x32_bf16 v[88:91], v[210:213], v[12:15], 0
	v_mfma_f32_16x16x32_bf16 v[104:107], v[210:213], v[16:19], 0
	v_mfma_f32_16x16x32_bf16 v[92:95], v[222:225], v[12:15], 0
	v_mfma_f32_16x16x32_bf16 v[108:111], v[222:225], v[16:19], 0
	v_mfma_f32_16x16x32_bf16 v[96:99], v[234:237], v[12:15], 0
	v_mfma_f32_16x16x32_bf16 v[112:115], v[234:237], v[16:19], 0
	ds_read_b128 v[198:201], v2 offset:13312
	ds_read_b128 v[210:213], v2 offset:14336
	ds_read_b128 v[222:225], v2 offset:15360
	ds_read_b128 v[234:237], v2 offset:16384
	s_waitcnt lgkmcnt(8)
	v_mfma_f32_16x16x32_bf16 v[84:87], v[202:205], v[4:7], v[84:87]
	v_mfma_f32_16x16x32_bf16 v[100:103], v[202:205], v[8:11], v[100:103]
	v_mfma_f32_16x16x32_bf16 v[88:91], v[214:217], v[4:7], v[88:91]
	v_mfma_f32_16x16x32_bf16 v[104:107], v[214:217], v[8:11], v[104:107]
	v_mfma_f32_16x16x32_bf16 v[92:95], v[226:229], v[4:7], v[92:95]
	v_mfma_f32_16x16x32_bf16 v[108:111], v[226:229], v[8:11], v[108:111]
	v_mfma_f32_16x16x32_bf16 v[96:99], v[238:241], v[4:7], v[96:99]
	v_mfma_f32_16x16x32_bf16 v[112:115], v[238:241], v[8:11], v[112:115]
	ds_read_b128 v[202:205], v2 offset:17408
	ds_read_b128 v[214:217], v2 offset:18432
	ds_read_b128 v[226:229], v2 offset:19456
	ds_read_b128 v[238:241], v2 offset:20480
	s_waitcnt lgkmcnt(8)
	v_mfma_f32_16x16x32_bf16 v[84:87], v[206:209], v[44:47], v[84:87]
	v_mfma_f32_16x16x32_bf16 v[100:103], v[206:209], v[60:63], v[100:103]
	v_mfma_f32_16x16x32_bf16 v[88:91], v[218:221], v[44:47], v[88:91]
	v_mfma_f32_16x16x32_bf16 v[104:107], v[218:221], v[60:63], v[104:107]
	v_mfma_f32_16x16x32_bf16 v[92:95], v[230:233], v[44:47], v[92:95]
	v_mfma_f32_16x16x32_bf16 v[108:111], v[230:233], v[60:63], v[108:111]
	v_mfma_f32_16x16x32_bf16 v[96:99], v[242:245], v[44:47], v[96:99]
	v_mfma_f32_16x16x32_bf16 v[112:115], v[242:245], v[60:63], v[112:115]
	s_cmp_gt_i32 s1, s30
	s_cbranch_scc0 .Lmla_nomask
	v_or_b32_e32 v166, s0, v0
	v_sub_u32_e32 v130, v151, v166
	v_sub_u32_e32 v131, v155, v166
	v_cmp_gt_i32_e64 s[38:39], 0, v130
	v_cmp_gt_i32_e64 s[40:41], 1, v130
	v_cmp_gt_i32_e64 s[42:43], 2, v130
	v_cmp_gt_i32_e64 s[44:45], 3, v130
	v_cmp_gt_i32_e64 s[46:47], 16, v130
	v_cmp_gt_i32_e64 s[48:49], 17, v130
	v_cmp_gt_i32_e64 s[50:51], 18, v130
	v_cmp_gt_i32_e64 s[52:53], 19, v130
	v_cndmask_b32_e64 v84, v84, v181, s[38:39]
	v_cndmask_b32_e64 v85, v85, v181, s[40:41]
	v_cndmask_b32_e64 v86, v86, v181, s[42:43]
	v_cndmask_b32_e64 v87, v87, v181, s[44:45]
	v_cndmask_b32_e64 v88, v88, v181, s[46:47]
	v_cndmask_b32_e64 v89, v89, v181, s[48:49]
	v_cndmask_b32_e64 v90, v90, v181, s[50:51]
	v_cndmask_b32_e64 v91, v91, v181, s[52:53]
	v_cmp_gt_i32_e64 s[38:39], 32, v130
	v_cmp_gt_i32_e64 s[40:41], 33, v130
	v_cmp_gt_i32_e64 s[42:43], 34, v130
	v_cmp_gt_i32_e64 s[44:45], 35, v130
	v_cmp_gt_i32_e64 s[46:47], 48, v130
	v_cmp_gt_i32_e64 s[48:49], 49, v130
	v_cmp_gt_i32_e64 s[50:51], 50, v130
	v_cmp_gt_i32_e64 s[52:53], 51, v130
	v_cndmask_b32_e64 v92, v92, v181, s[38:39]
	v_cndmask_b32_e64 v93, v93, v181, s[40:41]
	v_cndmask_b32_e64 v94, v94, v181, s[42:43]
	v_cndmask_b32_e64 v95, v95, v181, s[44:45]
	v_cndmask_b32_e64 v96, v96, v181, s[46:47]
	v_cndmask_b32_e64 v97, v97, v181, s[48:49]
	v_cndmask_b32_e64 v98, v98, v181, s[50:51]
	v_cndmask_b32_e64 v99, v99, v181, s[52:53]
	v_cmp_gt_i32_e64 s[38:39], 0, v131
	v_cmp_gt_i32_e64 s[40:41], 1, v131
	v_cmp_gt_i32_e64 s[42:43], 2, v131
	v_cmp_gt_i32_e64 s[44:45], 3, v131
	v_cmp_gt_i32_e64 s[46:47], 16, v131
	v_cmp_gt_i32_e64 s[48:49], 17, v131
	v_cmp_gt_i32_e64 s[50:51], 18, v131
	v_cmp_gt_i32_e64 s[52:53], 19, v131
	v_cndmask_b32_e64 v100, v100, v181, s[38:39]
	v_cndmask_b32_e64 v101, v101, v181, s[40:41]
	v_cndmask_b32_e64 v102, v102, v181, s[42:43]
	v_cndmask_b32_e64 v103, v103, v181, s[44:45]
	v_cndmask_b32_e64 v104, v104, v181, s[46:47]
	v_cndmask_b32_e64 v105, v105, v181, s[48:49]
	v_cndmask_b32_e64 v106, v106, v181, s[50:51]
	v_cndmask_b32_e64 v107, v107, v181, s[52:53]
	v_cmp_gt_i32_e64 s[38:39], 32, v131
	v_cmp_gt_i32_e64 s[40:41], 33, v131
	v_cmp_gt_i32_e64 s[42:43], 34, v131
	v_cmp_gt_i32_e64 s[44:45], 35, v131
	v_cmp_gt_i32_e64 s[46:47], 48, v131
	v_cmp_gt_i32_e64 s[48:49], 49, v131
	v_cmp_gt_i32_e64 s[50:51], 50, v131
	v_cmp_gt_i32_e64 s[52:53], 51, v131
	v_cndmask_b32_e64 v108, v108, v181, s[38:39]
	v_cndmask_b32_e64 v109, v109, v181, s[40:41]
	v_cndmask_b32_e64 v110, v110, v181, s[42:43]
	v_cndmask_b32_e64 v111, v111, v181, s[44:45]
	v_cndmask_b32_e64 v112, v112, v181, s[46:47]
	v_cndmask_b32_e64 v113, v113, v181, s[48:49]
	v_cndmask_b32_e64 v114, v114, v181, s[50:51]
	v_cndmask_b32_e64 v115, v115, v181, s[52:53]
; __device__ __forceinline__ void mla_unit(const Ctx& C, const Params& p, int unit) {
;     ...
;                 float mx = fmaxf(s[g][0][0], s[g][0][1]);
;                 mx = fmaxf(fmaxf(mx, s[g][0][2]), s[g][0][3]);
; #pragma unroll
;                 for (int blk = 1; blk < 4; ++blk) { mx = fmaxf(fmaxf(mx, s[g][blk][0]), s[g][blk][1]); mx = fmaxf(fmaxf(mx, s[g][blk][2]), s[g][blk][3]); }
;                 mx = rowmax4(mx);
;                 const float mn = fmaxf(m[g], mx * c2), alpha = __builtin_amdgcn_exp2f(m[g] - mn); m[g] = mn;
;                 f32x2 ps2 = (f32x2){0.f, 0.f};
;                 const f32x2 c2v = (f32x2){c2, c2}, mnv = (f32x2){mn, mn};
; #pragma unroll
;                 for (int blk = 0; blk < 4; ++blk)
; #pragma unroll
;                     for (int jp = 0; jp < 2; ++jp) { f32x2 x = (f32x2){s[g][blk][2 * jp], s[g][blk][2 * jp + 1]}; x = x * c2v - mnv;
;                         f32x2 pv; pv.x = __builtin_amdgcn_exp2f(x.x); pv.y = __builtin_amdgcn_exp2f(x.y); ps2 = ps2 + pv; s[g][blk][2 * jp] = pv.x; s[g][blk][2 * jp + 1] = pv.y; }
;                 const float ps = ps2.x + ps2.y;
;                 lsum[g] = lsum[g] * alpha + ps;
;                 if (__builtin_amdgcn_ballot_w64(alpha != 1.0f) != 0ull) {
; #pragma unroll
;                     for (int d = 0; d < 4; ++d) o[g][d] = o[g][d] * alpha;
;                 }
.Lmla_nomask:
	v_max3_f32 v130, v84, v85, v86
	v_max3_f32 v131, v100, v101, v102
	v_max3_f32 v130, v130, v87, v88
	v_max3_f32 v131, v131, v103, v104
	v_max3_f32 v130, v130, v89, v90
	v_max3_f32 v131, v131, v105, v106
	v_max3_f32 v130, v130, v91, v92
	v_max3_f32 v131, v131, v107, v108
	v_max3_f32 v130, v130, v93, v94
	v_max3_f32 v131, v131, v109, v110
	v_max3_f32 v130, v130, v95, v96
	v_max3_f32 v131, v131, v111, v112
	v_max3_f32 v130, v130, v97, v98
	v_max3_f32 v131, v131, v113, v114
	v_max_f32_e32 v130, v130, v99
	v_max_f32_e32 v131, v131, v115
	s_nop 1
	v_permlane16_swap_b32_e32 v130, v131
	v_max_f32_e32 v130, v130, v131
	v_mov_b32_e32 v131, v130
	s_nop 1
	v_permlane32_swap_b32_e32 v130, v131
	v_max_f32_e32 v130, v130, v131
	v_mov_b32_e32 v131, v130
	s_nop 1
	v_permlane16_swap_b32_e32 v130, v131
	v_mul_f32_e32 v130, 0x3e16c740, v130
	v_mul_f32_e32 v131, 0x3e16c740, v131
	v_max_f32_e32 v2, v152, v130
	v_max_f32_e32 v150, v154, v131
	v_sub_f32_e32 v130, v152, v2
	v_sub_f32_e32 v131, v154, v150
	v_exp_f32_e32 v152, v130
	v_exp_f32_e32 v154, v131
	v_pk_fma_f32 v[84:85], v[84:85], s[60:61], v[2:3] op_sel_hi:[1,0,0] neg_lo:[0,0,1] neg_hi:[0,0,1]
	v_pk_fma_f32 v[86:87], v[86:87], s[60:61], v[2:3] op_sel_hi:[1,0,0] neg_lo:[0,0,1] neg_hi:[0,0,1]
	v_cmp_neq_f32_e64 s[0:1], 1.0, v152
	v_cmp_neq_f32_e32 vcc, 1.0, v154
	v_pk_fma_f32 v[100:101], v[100:101], s[60:61], v[150:151] op_sel_hi:[1,0,0] neg_lo:[0,0,1] neg_hi:[0,0,1]
	v_pk_fma_f32 v[102:103], v[102:103], s[60:61], v[150:151] op_sel_hi:[1,0,0] neg_lo:[0,0,1] neg_hi:[0,0,1]
	v_pk_fma_f32 v[88:89], v[88:89], s[60:61], v[2:3] op_sel_hi:[1,0,0] neg_lo:[0,0,1] neg_hi:[0,0,1]
	v_pk_fma_f32 v[90:91], v[90:91], s[60:61], v[2:3] op_sel_hi:[1,0,0] neg_lo:[0,0,1] neg_hi:[0,0,1]
	v_pk_fma_f32 v[104:105], v[104:105], s[60:61], v[150:151] op_sel_hi:[1,0,0] neg_lo:[0,0,1] neg_hi:[0,0,1]
	v_pk_fma_f32 v[106:107], v[106:107], s[60:61], v[150:151] op_sel_hi:[1,0,0] neg_lo:[0,0,1] neg_hi:[0,0,1]
	s_or_b64 vcc, vcc, s[0:1]
	s_cbranch_vccz .Lmla_norescale
	v_pk_mul_f32 v[72:73], v[72:73], v[152:153] op_sel_hi:[1,0]
	v_pk_mul_f32 v[74:75], v[74:75], v[152:153] op_sel_hi:[1,0]
	v_pk_mul_f32 v[64:65], v[64:65], v[152:153] op_sel_hi:[1,0]
	v_pk_mul_f32 v[66:67], v[66:67], v[152:153] op_sel_hi:[1,0]
	v_pk_mul_f32 v[68:69], v[68:69], v[152:153] op_sel_hi:[1,0]
	v_pk_mul_f32 v[70:71], v[70:71], v[152:153] op_sel_hi:[1,0]
	v_pk_mul_f32 v[80:81], v[80:81], v[152:153] op_sel_hi:[1,0]
	v_pk_mul_f32 v[82:83], v[82:83], v[152:153] op_sel_hi:[1,0]
	v_pk_mul_f32 v[52:53], v[52:53], v[154:155] op_sel_hi:[1,0]
	v_pk_mul_f32 v[54:55], v[54:55], v[154:155] op_sel_hi:[1,0]
	v_pk_mul_f32 v[48:49], v[48:49], v[154:155] op_sel_hi:[1,0]
	v_pk_mul_f32 v[50:51], v[50:51], v[154:155] op_sel_hi:[1,0]
	v_pk_mul_f32 v[56:57], v[56:57], v[154:155] op_sel_hi:[1,0]
	v_pk_mul_f32 v[58:59], v[58:59], v[154:155] op_sel_hi:[1,0]
	v_pk_mul_f32 v[76:77], v[76:77], v[154:155] op_sel_hi:[1,0]
	v_pk_mul_f32 v[78:79], v[78:79], v[154:155] op_sel_hi:[1,0]
; #define LAS __attribute__((address_space(3)))
; __device__ __forceinline__ unsigned pkhw(float lo, float hi) { f32x2q v = {lo, hi}; bf16x2q b = __builtin_convertvector(v, bf16x2q); return __builtin_bit_cast(unsigned, b); }
; __device__ __forceinline__ void mla_unit(const Ctx& C, const Params& p, int unit) {
;     ...
;                     for (int jp = 0; jp < 2; ++jp) { f32x2 x = (f32x2){s[g][blk][2 * jp], s[g][blk][2 * jp + 1]}; x = x * c2v - mnv;
;                         f32x2 pv; pv.x = __builtin_amdgcn_exp2f(x.x); pv.y = __builtin_amdgcn_exp2f(x.y); ps2 = ps2 + pv; s[g][blk][2 * jp] = pv.x; s[g][blk][2 * jp + 1] = pv.y; }
;                 const float ps = ps2.x + ps2.y;
;                 lsum[g] = lsum[g] * alpha + ps;
;                 if (__builtin_amdgcn_ballot_w64(alpha != 1.0f) != 0ull) {
; #pragma unroll
;                     for (int d = 0; d < 4; ++d) o[g][d] = o[g][d] * alpha;
;                 }
; #pragma unroll
;                 for (int hf = 0; hf < 2; ++hf) { v4u pw; pw.x = pkhw(s[g][2 * hf][0], s[g][2 * hf][1]); pw.y = pkhw(s[g][2 * hf][2], s[g][2 * hf][3]); pw.z = pkhw(s[g][2 * hf + 1][0], s[g][2 * hf + 1][1]); pw.w = pkhw(s[g][2 * hf + 1][2], s[g][2 * hf + 1][3]);
;                     pf[g][hf] = __builtin_bit_cast(bf16x8, pw); }
;             }
; #pragma unroll
;             for (int hf = 0; hf < 2; ++hf)
; #pragma unroll
;                 for (int d = 0; d < 4; ++d) {
;                     const bf16x8 vf = *(const LAS bf16x8*)(Vb + (d * 16 + fr) * AV_ROW + (hf * 32 + fq * 8) * 2);
; #pragma unroll
;                     for (int g = 0; g < 2; ++g) o[g][d] = __builtin_amdgcn_mfma_f32_16x16x32_bf16(vf, pf[g][hf], o[g][d], 0, 0, 0);
;                 }
.Lmla_norescale:
	v_exp_f32_e32 v84, v84
	v_exp_f32_e32 v85, v85
	v_exp_f32_e32 v86, v86
	v_exp_f32_e32 v87, v87
	v_exp_f32_e32 v100, v100
	v_exp_f32_e32 v101, v101
	v_exp_f32_e32 v102, v102
	v_exp_f32_e32 v103, v103
	v_exp_f32_e32 v88, v88
	v_exp_f32_e32 v89, v89
	v_exp_f32_e32 v90, v90
	v_exp_f32_e32 v91, v91
	v_exp_f32_e32 v104, v104
	v_exp_f32_e32 v105, v105
	v_exp_f32_e32 v106, v106
	v_exp_f32_e32 v107, v107
	v_pk_add_f32 v[130:131], v[84:85], v[86:87]
	v_pk_add_f32 v[132:133], v[100:101], v[102:103]
	v_pk_add_f32 v[130:131], v[130:131], v[88:89]
	v_pk_add_f32 v[132:133], v[132:133], v[104:105]
	v_pk_add_f32 v[130:131], v[130:131], v[90:91]
	v_pk_add_f32 v[132:133], v[132:133], v[106:107]
	v_cvt_pk_bf16_f32 v84, v84, v85
	v_cvt_pk_bf16_f32 v85, v86, v87
	v_cvt_pk_bf16_f32 v86, v88, v89
	v_cvt_pk_bf16_f32 v87, v90, v91
	v_cvt_pk_bf16_f32 v100, v100, v101
	v_cvt_pk_bf16_f32 v101, v102, v103
	v_cvt_pk_bf16_f32 v102, v104, v105
	v_cvt_pk_bf16_f32 v103, v106, v107
	s_waitcnt lgkmcnt(4)
	v_mfma_f32_16x16x32_bf16 v[72:75], v[198:201], v[84:87], v[72:75]
	v_pk_fma_f32 v[92:93], v[92:93], s[60:61], v[2:3] op_sel_hi:[1,0,0] neg_lo:[0,0,1] neg_hi:[0,0,1]
	v_pk_fma_f32 v[94:95], v[94:95], s[60:61], v[2:3] op_sel_hi:[1,0,0] neg_lo:[0,0,1] neg_hi:[0,0,1]
	v_pk_fma_f32 v[108:109], v[108:109], s[60:61], v[150:151] op_sel_hi:[1,0,0] neg_lo:[0,0,1] neg_hi:[0,0,1]
	v_pk_fma_f32 v[110:111], v[110:111], s[60:61], v[150:151] op_sel_hi:[1,0,0] neg_lo:[0,0,1] neg_hi:[0,0,1]
	v_pk_fma_f32 v[96:97], v[96:97], s[60:61], v[2:3] op_sel_hi:[1,0,0] neg_lo:[0,0,1] neg_hi:[0,0,1]
	v_pk_fma_f32 v[98:99], v[98:99], s[60:61], v[2:3] op_sel_hi:[1,0,0] neg_lo:[0,0,1] neg_hi:[0,0,1]
	v_mfma_f32_16x16x32_bf16 v[52:55], v[198:201], v[100:103], v[52:55]
	v_pk_fma_f32 v[112:113], v[112:113], s[60:61], v[150:151] op_sel_hi:[1,0,0] neg_lo:[0,0,1] neg_hi:[0,0,1]
	v_pk_fma_f32 v[114:115], v[114:115], s[60:61], v[150:151] op_sel_hi:[1,0,0] neg_lo:[0,0,1] neg_hi:[0,0,1]
	v_exp_f32_e32 v92, v92
	v_exp_f32_e32 v93, v93
	v_exp_f32_e32 v94, v94
	v_exp_f32_e32 v95, v95
	v_mfma_f32_16x16x32_bf16 v[64:67], v[210:213], v[84:87], v[64:67]
	v_exp_f32_e32 v108, v108
	v_exp_f32_e32 v109, v109
	v_exp_f32_e32 v110, v110
	v_exp_f32_e32 v111, v111
	v_exp_f32_e32 v96, v96
	v_exp_f32_e32 v97, v97
	v_mfma_f32_16x16x32_bf16 v[48:51], v[210:213], v[100:103], v[48:51]
	v_exp_f32_e32 v98, v98
	v_exp_f32_e32 v99, v99
	v_exp_f32_e32 v112, v112
	v_exp_f32_e32 v113, v113
	v_exp_f32_e32 v114, v114
	v_exp_f32_e32 v115, v115
	v_mfma_f32_16x16x32_bf16 v[68:71], v[222:225], v[84:87], v[68:71]
	v_pk_add_f32 v[130:131], v[130:131], v[92:93]
	v_pk_add_f32 v[132:133], v[132:133], v[108:109]
	v_pk_add_f32 v[130:131], v[130:131], v[94:95]
	v_pk_add_f32 v[132:133], v[132:133], v[110:111]
	v_pk_add_f32 v[130:131], v[130:131], v[96:97]
	v_pk_add_f32 v[132:133], v[132:133], v[112:113]
	v_mfma_f32_16x16x32_bf16 v[56:59], v[222:225], v[100:103], v[56:59]
	v_pk_add_f32 v[130:131], v[130:131], v[98:99]
	v_pk_add_f32 v[132:133], v[132:133], v[114:115]
	v_add_f32_e32 v130, v130, v131
	v_add_f32_e32 v132, v132, v133
	v_fma_f32 v190, v190, v152, v130
	v_fma_f32 v191, v191, v154, v132
	v_mfma_f32_16x16x32_bf16 v[80:83], v[234:237], v[84:87], v[80:83]
	v_cvt_pk_bf16_f32 v92, v92, v93
	v_cvt_pk_bf16_f32 v93, v94, v95
	v_cvt_pk_bf16_f32 v94, v96, v97
	v_cvt_pk_bf16_f32 v95, v98, v99
	v_cvt_pk_bf16_f32 v108, v108, v109
	v_cvt_pk_bf16_f32 v109, v110, v111
	v_mfma_f32_16x16x32_bf16 v[76:79], v[234:237], v[100:103], v[76:79]
	v_cvt_pk_bf16_f32 v110, v112, v113
	v_cvt_pk_bf16_f32 v111, v114, v115
	s_waitcnt lgkmcnt(0)
	v_mfma_f32_16x16x32_bf16 v[72:75], v[202:205], v[92:95], v[72:75]
	v_mfma_f32_16x16x32_bf16 v[52:55], v[202:205], v[108:111], v[52:55]
	v_mfma_f32_16x16x32_bf16 v[64:67], v[214:217], v[92:95], v[64:67]
	v_mfma_f32_16x16x32_bf16 v[48:51], v[214:217], v[108:111], v[48:51]
	v_mfma_f32_16x16x32_bf16 v[68:71], v[226:229], v[92:95], v[68:71]
	v_mfma_f32_16x16x32_bf16 v[56:59], v[226:229], v[108:111], v[56:59]
	v_mfma_f32_16x16x32_bf16 v[80:83], v[238:241], v[92:95], v[80:83]
	v_mfma_f32_16x16x32_bf16 v[76:79], v[238:241], v[108:111], v[76:79]
